# down-proj phase: residual tile of the fused final-norm epilogue prefetched into L2 three K-iterations before the loop ends
# baseline (speedup 1.0000x reference)
; #define PG8_STAGE(bufoff, gbase, RR, ld) do { _Pragma("unroll") for (int _i = 0; _i < 2; ++_i) \
;         __builtin_amdgcn_global_load_lds((const unsigned*)((const char*)(gbase) + (RR)[_i] * (ld) + C2[_i]), (LAS unsigned*)(lds + (bufoff) + ldsw + _i * 8192), 16, 0, 0); } while (0)
; #define PG8_LDA(dst, b, h) do { _Pragma("unroll") for (int m = 0; m < 4; ++m) _Pragma("unroll") for (int k = 0; k < 2; ++k) dst[m][k] = *(const LAS bf16x8*)(lds + PG8_SA(b, h) + aoff + m * 2048 + k * 1024); } while (0)
; #define PG8_LDB(dst, b, h) do { _Pragma("unroll") for (int n = 0; n < 2; ++n) _Pragma("unroll") for (int k = 0; k < 2; ++k) dst[n][k] = *(const LAS bf16x8*)(lds + PG8_SB(b, h) + boff + n * 2048 + k * 1024); } while (0)
; #define PG8_MMA(ai, bj, At, Bt) do { __builtin_amdgcn_s_setprio(1); _Pragma("unroll") for (int m = 0; m < 4; ++m) _Pragma("unroll") for (int n = 0; n < 2; ++n) _Pragma("unroll") for (int k = 0; k < 2; ++k) \
;         acc[ai][bj][m][n] = __builtin_amdgcn_mfma_f32_16x16x32_bf16(Bt[n][k], At[m][k], acc[ai][bj][m][n], 0, 0, 0); __builtin_amdgcn_s_setprio(0); } while (0)
; #define PG8_BAR __builtin_amdgcn_s_barrier()
; template <class Sched, class Epi>
; __device__ __forceinline__ void gemm_run(LAS unsigned char* lds, const Sched& S, const Epi& E) {
;     ...
;             PG8_LDB(B0, 0, 0); PG8_LDB(B1, 0, 1); PG8_SCHED; PG8_LDA(At, 0, 0); PG8_STAGE(PG8_SA(1, 1), a1 + (size_t)HALF * lda, RA, lda);
;             PG8_WAIT_V(8); PG8_WAIT_L(0); PG8_BAR; PG8_MMA(0, 0, At, B0); PG8_MMA(0, 1, At, B1); PG8_BAR; PG8_SCHED;
;             PG8_LDA(At, 0, 1); PG8_STAGE(PG8_SB(0, 0), b2, RB, lb2); PG8_STAGE(PG8_SB(0, 1), b2 + (size_t)HALF * lb2, RB, lb2); PG8_STAGE(PG8_SA(0, 0), a2, RA, la2);
;             PG8_WAIT_V(8); PG8_WAIT_L(0); PG8_BAR; PG8_MMA(1, 0, At, B0); PG8_MMA(1, 1, At, B1); PG8_BAR; PG8_SCHED;
;             PG8_LDB(B0, 1, 0); PG8_LDB(B1, 1, 1); PG8_SCHED; PG8_LDA(At, 1, 0); PG8_STAGE(PG8_SA(0, 1), a2 + (size_t)HALF * la2, RA, la2);
;             PG8_WAIT_V(8); PG8_WAIT_L(0); PG8_BAR; PG8_MMA(0, 0, At, B0); PG8_MMA(0, 1, At, B1); PG8_BAR; PG8_SCHED;
;             PG8_LDA(At, 1, 1); PG8_STAGE(PG8_SB(1, 0), b3, RB, lb2); PG8_STAGE(PG8_SB(1, 1), b3 + (size_t)HALF * lb2, RB, lb2); PG8_STAGE(PG8_SA(1, 0), a3, RA, la2);
;             PG8_WAIT_V(8); PG8_WAIT_L(0); PG8_BAR; PG8_MMA(1, 0, At, B0); PG8_MMA(1, 1, At, B1); PG8_BAR; PG8_SCHED;
.LBB0_1068:
	v_add_u32_e32 v151, s50, v149
	ds_read_b128 v[152:155], v151
	ds_read_b128 v[156:159], v151 offset:1024
	ds_read_b128 v[160:163], v151 offset:2048
	ds_read_b128 v[164:167], v151 offset:3072
	v_add_u32_e32 v151, s51, v149
	s_add_u32 s30, s20, s28
	ds_read_b128 v[168:171], v151
	ds_read_b128 v[172:175], v151 offset:1024
	ds_read_b128 v[176:179], v151 offset:2048
	ds_read_b128 v[180:183], v151 offset:3072
	s_addc_u32 s31, s21, s29
	s_mov_b32 s98, s30
	s_mov_b32 s99, s31
	s_add_u32 s30, s30, 0x100
	s_addc_u32 s31, s31, 0
	s_add_u32 s68, s65, s28
	s_addc_u32 s69, s66, s29
	s_cmpk_eq_i32 s28, 0x2b00
	s_cselect_b32 s37, s17, s31
	s_cselect_b32 s36, s16, s30
	s_cselect_b32 s31, s19, s69
	s_cselect_b32 s30, s18, s68
	s_mov_b64 s[100:101], s[36:37]
	s_cmpk_eq_i32 s67, 80
	s_cbranch_scc1 .Lpf9
.Lpf9_back:
	s_mov_b32 m0, s52
	ds_read_b128 v[190:193], v150
	ds_read_b128 v[194:197], v150 offset:1024
	ds_read_b128 v[198:201], v150 offset:2048
	ds_read_b128 v[202:205], v150 offset:3072
	ds_read_b128 v[206:209], v150 offset:4096
	ds_read_b128 v[210:213], v150 offset:5120
	ds_read_b128 v[214:217], v150 offset:6144
	ds_read_b128 v[218:221], v150 offset:7168
	global_load_lds_dwordx4 v140, s[98:99]
	s_mov_b32 m0, s53
	s_nop 0
	global_load_lds_dwordx4 v142, s[98:99]
	s_waitcnt vmcnt(8)
	s_waitcnt lgkmcnt(0)
	s_barrier
	s_waitcnt lgkmcnt(0)
	v_mfma_f32_16x16x32_bf16 v[126:129], v[152:155], v[190:193], v[126:129]
	v_mfma_f32_16x16x32_bf16 v[122:125], v[160:163], v[190:193], v[122:125]
	v_mfma_f32_16x16x32_bf16 v[110:113], v[152:155], v[198:201], v[110:113]
	v_mfma_f32_16x16x32_bf16 v[106:109], v[160:163], v[198:201], v[106:109]
	v_mfma_f32_16x16x32_bf16 v[94:97], v[152:155], v[206:209], v[94:97]
	v_mfma_f32_16x16x32_bf16 v[90:93], v[160:163], v[206:209], v[90:93]
	v_mfma_f32_16x16x32_bf16 v[78:81], v[152:155], v[214:217], v[78:81]
	v_mfma_f32_16x16x32_bf16 v[74:77], v[160:163], v[214:217], v[74:77]
	v_mfma_f32_16x16x32_bf16 v[126:129], v[156:159], v[194:197], v[126:129]
	v_mfma_f32_16x16x32_bf16 v[122:125], v[164:167], v[194:197], v[122:125]
	v_mfma_f32_16x16x32_bf16 v[110:113], v[156:159], v[202:205], v[110:113]
	v_mfma_f32_16x16x32_bf16 v[106:109], v[164:167], v[202:205], v[106:109]
	v_mfma_f32_16x16x32_bf16 v[94:97], v[156:159], v[210:213], v[94:97]
	v_mfma_f32_16x16x32_bf16 v[90:93], v[164:167], v[210:213], v[90:93]
	v_mfma_f32_16x16x32_bf16 v[78:81], v[156:159], v[218:221], v[78:81]
	v_mfma_f32_16x16x32_bf16 v[74:77], v[164:167], v[218:221], v[74:77]
	v_mfma_f32_16x16x32_bf16 v[118:121], v[168:171], v[190:193], v[118:121]
	v_mfma_f32_16x16x32_bf16 v[114:117], v[176:179], v[190:193], v[114:117]
	v_mfma_f32_16x16x32_bf16 v[102:105], v[168:171], v[198:201], v[102:105]
	v_mfma_f32_16x16x32_bf16 v[98:101], v[176:179], v[198:201], v[98:101]
	v_mfma_f32_16x16x32_bf16 v[86:89], v[168:171], v[206:209], v[86:89]
	v_mfma_f32_16x16x32_bf16 v[82:85], v[176:179], v[206:209], v[82:85]
	v_mfma_f32_16x16x32_bf16 v[70:73], v[168:171], v[214:217], v[70:73]
	v_mfma_f32_16x16x32_bf16 v[66:69], v[176:179], v[214:217], v[66:69]
	v_mfma_f32_16x16x32_bf16 v[118:121], v[172:175], v[194:197], v[118:121]
	v_mfma_f32_16x16x32_bf16 v[114:117], v[180:183], v[194:197], v[114:117]
	v_mfma_f32_16x16x32_bf16 v[102:105], v[172:175], v[202:205], v[102:105]
	v_mfma_f32_16x16x32_bf16 v[98:101], v[180:183], v[202:205], v[98:101]
	v_mfma_f32_16x16x32_bf16 v[86:89], v[172:175], v[210:213], v[86:89]
	v_mfma_f32_16x16x32_bf16 v[82:85], v[180:183], v[210:213], v[82:85]
	v_mfma_f32_16x16x32_bf16 v[70:73], v[172:175], v[218:221], v[70:73]
	v_mfma_f32_16x16x32_bf16 v[66:69], v[180:183], v[218:221], v[66:69]
	s_barrier
	s_add_u32 s68, s30, 0x160000
	s_mov_b32 m0, s54
	s_addc_u32 s69, s31, 0
	ds_read_b128 v[190:193], v150 offset:16384
	ds_read_b128 v[194:197], v150 offset:17408
	ds_read_b128 v[198:201], v150 offset:18432
	ds_read_b128 v[202:205], v150 offset:19456
	ds_read_b128 v[206:209], v150 offset:20480
	ds_read_b128 v[210:213], v150 offset:21504
	ds_read_b128 v[214:217], v150 offset:22528
	ds_read_b128 v[218:221], v150 offset:23552
	global_load_lds_dwordx4 v132, s[30:31]
	s_mov_b32 m0, s55
	s_nop 0
	global_load_lds_dwordx4 v134, s[30:31]
	s_mov_b32 m0, s56
	s_nop 0
	global_load_lds_dwordx4 v132, s[68:69]
	s_mov_b32 m0, s57
	s_nop 0
	global_load_lds_dwordx4 v134, s[68:69]
	s_mov_b32 m0, s42
	s_nop 0
	global_load_lds_dwordx4 v136, s[36:37]
	s_mov_b32 m0, s43
	s_nop 0
	global_load_lds_dwordx4 v138, s[36:37]
	s_waitcnt vmcnt(8)
	s_waitcnt lgkmcnt(0)
	s_barrier
	s_waitcnt lgkmcnt(0)
	v_mfma_f32_16x16x32_bf16 v[62:65], v[152:155], v[190:193], v[62:65]
	v_mfma_f32_16x16x32_bf16 v[58:61], v[160:163], v[190:193], v[58:61]
	v_mfma_f32_16x16x32_bf16 v[46:49], v[152:155], v[198:201], v[46:49]
	v_mfma_f32_16x16x32_bf16 v[42:45], v[160:163], v[198:201], v[42:45]
	v_mfma_f32_16x16x32_bf16 v[30:33], v[152:155], v[206:209], v[30:33]
	v_mfma_f32_16x16x32_bf16 v[26:29], v[160:163], v[206:209], v[26:29]
	v_mfma_f32_16x16x32_bf16 v[14:17], v[152:155], v[214:217], v[14:17]
	v_mfma_f32_16x16x32_bf16 v[10:13], v[160:163], v[214:217], v[10:13]
	v_mfma_f32_16x16x32_bf16 v[62:65], v[156:159], v[194:197], v[62:65]
	v_mfma_f32_16x16x32_bf16 v[58:61], v[164:167], v[194:197], v[58:61]
	v_mfma_f32_16x16x32_bf16 v[46:49], v[156:159], v[202:205], v[46:49]
	v_mfma_f32_16x16x32_bf16 v[42:45], v[164:167], v[202:205], v[42:45]
	v_mfma_f32_16x16x32_bf16 v[30:33], v[156:159], v[210:213], v[30:33]
	v_mfma_f32_16x16x32_bf16 v[26:29], v[164:167], v[210:213], v[26:29]
	v_mfma_f32_16x16x32_bf16 v[14:17], v[156:159], v[218:221], v[14:17]
	v_mfma_f32_16x16x32_bf16 v[10:13], v[164:167], v[218:221], v[10:13]
	v_mfma_f32_16x16x32_bf16 v[54:57], v[168:171], v[190:193], v[54:57]
	v_mfma_f32_16x16x32_bf16 v[50:53], v[176:179], v[190:193], v[50:53]
	v_mfma_f32_16x16x32_bf16 v[38:41], v[168:171], v[198:201], v[38:41]
	v_mfma_f32_16x16x32_bf16 v[34:37], v[176:179], v[198:201], v[34:37]
	v_mfma_f32_16x16x32_bf16 v[22:25], v[168:171], v[206:209], v[22:25]
	v_mfma_f32_16x16x32_bf16 v[18:21], v[176:179], v[206:209], v[18:21]
	v_mfma_f32_16x16x32_bf16 v[6:9], v[168:171], v[214:217], v[6:9]
	v_mfma_f32_16x16x32_bf16 v[2:5], v[176:179], v[214:217], v[2:5]
	v_mfma_f32_16x16x32_bf16 v[54:57], v[172:175], v[194:197], v[54:57]
	v_mfma_f32_16x16x32_bf16 v[50:53], v[180:183], v[194:197], v[50:53]
	v_mfma_f32_16x16x32_bf16 v[38:41], v[172:175], v[202:205], v[38:41]
	v_mfma_f32_16x16x32_bf16 v[34:37], v[180:183], v[202:205], v[34:37]
	v_mfma_f32_16x16x32_bf16 v[22:25], v[172:175], v[210:213], v[22:25]
	v_mfma_f32_16x16x32_bf16 v[18:21], v[180:183], v[210:213], v[18:21]
	v_mfma_f32_16x16x32_bf16 v[6:9], v[172:175], v[218:221], v[6:9]
	v_mfma_f32_16x16x32_bf16 v[2:5], v[180:183], v[218:221], v[2:5]
	s_barrier
; #define PG8_STAGE(bufoff, gbase, RR, ld) do { _Pragma("unroll") for (int _i = 0; _i < 2; ++_i) \
;         __builtin_amdgcn_global_load_lds((const unsigned*)((const char*)(gbase) + (RR)[_i] * (ld) + C2[_i]), (LAS unsigned*)(lds + (bufoff) + ldsw + _i * 8192), 16, 0, 0); } while (0)
; #define PG8_LDA(dst, b, h) do { _Pragma("unroll") for (int m = 0; m < 4; ++m) _Pragma("unroll") for (int k = 0; k < 2; ++k) dst[m][k] = *(const LAS bf16x8*)(lds + PG8_SA(b, h) + aoff + m * 2048 + k * 1024); } while (0)
; #define PG8_LDB(dst, b, h) do { _Pragma("unroll") for (int n = 0; n < 2; ++n) _Pragma("unroll") for (int k = 0; k < 2; ++k) dst[n][k] = *(const LAS bf16x8*)(lds + PG8_SB(b, h) + boff + n * 2048 + k * 1024); } while (0)
; #define PG8_MMA(ai, bj, At, Bt) do { __builtin_amdgcn_s_setprio(1); _Pragma("unroll") for (int m = 0; m < 4; ++m) _Pragma("unroll") for (int n = 0; n < 2; ++n) _Pragma("unroll") for (int k = 0; k < 2; ++k) \
;         acc[ai][bj][m][n] = __builtin_amdgcn_mfma_f32_16x16x32_bf16(Bt[n][k], At[m][k], acc[ai][bj][m][n], 0, 0, 0); __builtin_amdgcn_s_setprio(0); } while (0)
; #define PG8_WAIT_V(n) asm volatile("s_waitcnt vmcnt(" #n ")" ::: "memory")
; #define PG8_WAIT_L(n) asm volatile("s_waitcnt lgkmcnt(" #n ")" ::: "memory")
; #define PG8_BAR __builtin_amdgcn_s_barrier()
; #define PG8_SCHED __builtin_amdgcn_sched_barrier(0)
; template <class Sched, class Epi>
; __device__ __forceinline__ void gemm_run(LAS unsigned char* lds, const Sched& S, const Epi& E) {
;     ...
;             PG8_LDA(At, 0, 1); PG8_STAGE(PG8_SB(0, 0), b2, RB, lb2); PG8_STAGE(PG8_SB(0, 1), b2 + (size_t)HALF * lb2, RB, lb2); PG8_STAGE(PG8_SA(0, 0), a2, RA, la2);
;             PG8_WAIT_V(8); PG8_WAIT_L(0); PG8_BAR; PG8_MMA(1, 0, At, B0); PG8_MMA(1, 1, At, B1); PG8_BAR; PG8_SCHED;
;             PG8_LDB(B0, 1, 0); PG8_LDB(B1, 1, 1); PG8_SCHED; PG8_LDA(At, 1, 0); PG8_STAGE(PG8_SA(0, 1), a2 + (size_t)HALF * la2, RA, la2);
;             PG8_WAIT_V(8); PG8_WAIT_L(0); PG8_BAR; PG8_MMA(0, 0, At, B0); PG8_MMA(0, 1, At, B1); PG8_BAR; PG8_SCHED;
;             PG8_LDA(At, 1, 1); PG8_STAGE(PG8_SB(1, 0), b3, RB, lb2); PG8_STAGE(PG8_SB(1, 1), b3 + (size_t)HALF * lb2, RB, lb2); PG8_STAGE(PG8_SA(1, 0), a3, RA, la2);
;             PG8_WAIT_V(8); PG8_WAIT_L(0); PG8_BAR; PG8_MMA(1, 0, At, B0); PG8_MMA(1, 1, At, B1); PG8_BAR; PG8_SCHED;
;         }
;         if (wr == 0) PG8_BAR;
	v_add_u32_e32 v151, s58, v149
	ds_read_b128 v[152:155], v151
	ds_read_b128 v[156:159], v151 offset:1024
	ds_read_b128 v[160:163], v151 offset:2048
	ds_read_b128 v[164:167], v151 offset:3072
	v_add_u32_e32 v151, s59, v149
	ds_read_b128 v[168:171], v151
	ds_read_b128 v[172:175], v151 offset:1024
	ds_read_b128 v[176:179], v151 offset:2048
	ds_read_b128 v[180:183], v151 offset:3072
	s_add_u32 s36, s36, 0x160000
	s_addc_u32 s37, s37, 0
	s_mov_b32 m0, s44
	ds_read_b128 v[190:193], v150 offset:32768
	ds_read_b128 v[194:197], v150 offset:33792
	ds_read_b128 v[198:201], v150 offset:34816
	ds_read_b128 v[202:205], v150 offset:35840
	ds_read_b128 v[206:209], v150 offset:36864
	ds_read_b128 v[210:213], v150 offset:37888
	ds_read_b128 v[214:217], v150 offset:38912
	ds_read_b128 v[218:221], v150 offset:39936
	global_load_lds_dwordx4 v136, s[36:37]
	s_mov_b32 m0, s45
	s_nop 0
	global_load_lds_dwordx4 v138, s[36:37]
	s_waitcnt vmcnt(8)
	s_waitcnt lgkmcnt(0)
	s_barrier
	s_waitcnt lgkmcnt(0)
	v_mfma_f32_16x16x32_bf16 v[126:129], v[152:155], v[190:193], v[126:129]
	v_mfma_f32_16x16x32_bf16 v[122:125], v[160:163], v[190:193], v[122:125]
	v_mfma_f32_16x16x32_bf16 v[110:113], v[152:155], v[198:201], v[110:113]
	v_mfma_f32_16x16x32_bf16 v[106:109], v[160:163], v[198:201], v[106:109]
	v_mfma_f32_16x16x32_bf16 v[94:97], v[152:155], v[206:209], v[94:97]
	v_mfma_f32_16x16x32_bf16 v[90:93], v[160:163], v[206:209], v[90:93]
	v_mfma_f32_16x16x32_bf16 v[78:81], v[152:155], v[214:217], v[78:81]
	v_mfma_f32_16x16x32_bf16 v[74:77], v[160:163], v[214:217], v[74:77]
	v_mfma_f32_16x16x32_bf16 v[126:129], v[156:159], v[194:197], v[126:129]
	v_mfma_f32_16x16x32_bf16 v[122:125], v[164:167], v[194:197], v[122:125]
	v_mfma_f32_16x16x32_bf16 v[110:113], v[156:159], v[202:205], v[110:113]
	v_mfma_f32_16x16x32_bf16 v[106:109], v[164:167], v[202:205], v[106:109]
	v_mfma_f32_16x16x32_bf16 v[94:97], v[156:159], v[210:213], v[94:97]
	v_mfma_f32_16x16x32_bf16 v[90:93], v[164:167], v[210:213], v[90:93]
	v_mfma_f32_16x16x32_bf16 v[78:81], v[156:159], v[218:221], v[78:81]
	v_mfma_f32_16x16x32_bf16 v[74:77], v[164:167], v[218:221], v[74:77]
	v_mfma_f32_16x16x32_bf16 v[118:121], v[168:171], v[190:193], v[118:121]
	v_mfma_f32_16x16x32_bf16 v[114:117], v[176:179], v[190:193], v[114:117]
	v_mfma_f32_16x16x32_bf16 v[102:105], v[168:171], v[198:201], v[102:105]
	v_mfma_f32_16x16x32_bf16 v[98:101], v[176:179], v[198:201], v[98:101]
	v_mfma_f32_16x16x32_bf16 v[86:89], v[168:171], v[206:209], v[86:89]
	v_mfma_f32_16x16x32_bf16 v[82:85], v[176:179], v[206:209], v[82:85]
	v_mfma_f32_16x16x32_bf16 v[70:73], v[168:171], v[214:217], v[70:73]
	v_mfma_f32_16x16x32_bf16 v[66:69], v[176:179], v[214:217], v[66:69]
	v_mfma_f32_16x16x32_bf16 v[118:121], v[172:175], v[194:197], v[118:121]
	v_mfma_f32_16x16x32_bf16 v[114:117], v[180:183], v[194:197], v[114:117]
	v_mfma_f32_16x16x32_bf16 v[102:105], v[172:175], v[202:205], v[102:105]
	v_mfma_f32_16x16x32_bf16 v[98:101], v[180:183], v[202:205], v[98:101]
	v_mfma_f32_16x16x32_bf16 v[86:89], v[172:175], v[210:213], v[86:89]
	v_mfma_f32_16x16x32_bf16 v[82:85], v[180:183], v[210:213], v[82:85]
	v_mfma_f32_16x16x32_bf16 v[70:73], v[172:175], v[218:221], v[70:73]
	v_mfma_f32_16x16x32_bf16 v[66:69], v[180:183], v[218:221], v[66:69]
	s_barrier
	s_mov_b32 m0, s60
	ds_read_b128 v[190:193], v150 offset:49152
	ds_read_b128 v[194:197], v150 offset:50176
	ds_read_b128 v[198:201], v150 offset:51200
	ds_read_b128 v[202:205], v150 offset:52224
	ds_read_b128 v[206:209], v150 offset:53248
	ds_read_b128 v[210:213], v150 offset:54272
	ds_read_b128 v[214:217], v150 offset:55296
	ds_read_b128 v[218:221], v150 offset:56320
	s_add_u32 s98, s30, 0x80
	s_addc_u32 s99, s31, 0
	global_load_lds_dwordx4 v132, s[98:99]
	s_add_i32 m0, s60, 0x2000
	s_nop 0
	global_load_lds_dwordx4 v134, s[98:99]
	s_add_u32 s30, s30, 0x160080
	s_addc_u32 s31, s31, 0
	s_add_i32 s36, s59, s35
	s_mov_b32 m0, s36
	s_nop 0
	global_load_lds_dwordx4 v132, s[30:31]
	s_add_i32 m0, s36, 0x2000
	s_nop 0
	global_load_lds_dwordx4 v134, s[30:31]
	s_mov_b32 m0, s47
	s_nop 0
	s_add_u32 s100, s100, 0x80
	s_addc_u32 s101, s101, 0
	global_load_lds_dwordx4 v136, s[100:101]
	s_mov_b32 m0, s48
	s_nop 0
	global_load_lds_dwordx4 v138, s[100:101]
	s_waitcnt vmcnt(8)
	s_waitcnt lgkmcnt(0)
	s_barrier
	s_waitcnt lgkmcnt(0)
	v_mfma_f32_16x16x32_bf16 v[62:65], v[152:155], v[190:193], v[62:65]
	v_mfma_f32_16x16x32_bf16 v[58:61], v[160:163], v[190:193], v[58:61]
	v_mfma_f32_16x16x32_bf16 v[46:49], v[152:155], v[198:201], v[46:49]
	v_mfma_f32_16x16x32_bf16 v[42:45], v[160:163], v[198:201], v[42:45]
	v_mfma_f32_16x16x32_bf16 v[30:33], v[152:155], v[206:209], v[30:33]
	v_mfma_f32_16x16x32_bf16 v[26:29], v[160:163], v[206:209], v[26:29]
	v_mfma_f32_16x16x32_bf16 v[14:17], v[152:155], v[214:217], v[14:17]
	v_mfma_f32_16x16x32_bf16 v[10:13], v[160:163], v[214:217], v[10:13]
	v_mfma_f32_16x16x32_bf16 v[62:65], v[156:159], v[194:197], v[62:65]
	v_mfma_f32_16x16x32_bf16 v[58:61], v[164:167], v[194:197], v[58:61]
	v_mfma_f32_16x16x32_bf16 v[46:49], v[156:159], v[202:205], v[46:49]
	v_mfma_f32_16x16x32_bf16 v[42:45], v[164:167], v[202:205], v[42:45]
	v_mfma_f32_16x16x32_bf16 v[30:33], v[156:159], v[210:213], v[30:33]
	v_mfma_f32_16x16x32_bf16 v[26:29], v[164:167], v[210:213], v[26:29]
	v_mfma_f32_16x16x32_bf16 v[14:17], v[156:159], v[218:221], v[14:17]
	v_mfma_f32_16x16x32_bf16 v[10:13], v[164:167], v[218:221], v[10:13]
	v_mfma_f32_16x16x32_bf16 v[54:57], v[168:171], v[190:193], v[54:57]
	v_mfma_f32_16x16x32_bf16 v[50:53], v[176:179], v[190:193], v[50:53]
	v_mfma_f32_16x16x32_bf16 v[38:41], v[168:171], v[198:201], v[38:41]
	v_mfma_f32_16x16x32_bf16 v[34:37], v[176:179], v[198:201], v[34:37]
	v_mfma_f32_16x16x32_bf16 v[22:25], v[168:171], v[206:209], v[22:25]
	v_mfma_f32_16x16x32_bf16 v[18:21], v[176:179], v[206:209], v[18:21]
	v_mfma_f32_16x16x32_bf16 v[6:9], v[168:171], v[214:217], v[6:9]
	v_mfma_f32_16x16x32_bf16 v[2:5], v[176:179], v[214:217], v[2:5]
	v_mfma_f32_16x16x32_bf16 v[54:57], v[172:175], v[194:197], v[54:57]
	v_mfma_f32_16x16x32_bf16 v[50:53], v[180:183], v[194:197], v[50:53]
	v_mfma_f32_16x16x32_bf16 v[38:41], v[172:175], v[202:205], v[38:41]
	v_mfma_f32_16x16x32_bf16 v[34:37], v[180:183], v[202:205], v[34:37]
	v_mfma_f32_16x16x32_bf16 v[22:25], v[172:175], v[210:213], v[22:25]
	v_mfma_f32_16x16x32_bf16 v[18:21], v[180:183], v[210:213], v[18:21]
	v_mfma_f32_16x16x32_bf16 v[6:9], v[172:175], v[218:221], v[6:9]
	v_mfma_f32_16x16x32_bf16 v[2:5], v[180:183], v[218:221], v[2:5]
	s_barrier
	s_add_i32 s67, s67, 2
	s_add_u32 s28, s28, 0x100
	s_addc_u32 s29, s29, 0
	s_cmpk_gt_u32 s67, 0x55
	s_cbranch_scc0 .LBB0_1068
	s_and_b64 vcc, exec, s[12:13]
	s_cbranch_vccz .LBB0_1071
	s_barrier

; #define SBAR() __builtin_amdgcn_sched_barrier(0)
;     __device__ __forceinline__ void fused(f32x4 (&acc)[2][2][4][2], const Unit& u, int wr, int wc, int fr, int fq, LAS unsigned char* lds, int wid, int lane) const {
;     ...
;         u32x4 hv[8][2];
; #pragma unroll
;         for (int i = 0; i < 8; ++i)
; #pragma unroll
;             for (int bj = 0; bj < 2; ++bj) hv[i][bj] = *(const u32x4*)(P.h1b_() + (size_t)(u.pm * 256 + (i >> 2) * 128 + wr * 64 + (i & 3) * 16 + fr) * DM + u.pn * 256 + bj * 128 + c8);
;         SBAR();
.Lpf9:
	s_lshl_b32 s10, s0, 20
	s_lshl_b32 s11, s49, 9
	s_add_i32 s10, s10, s11
	s_add_i32 s10, s10, 0x400000
	s_add_u32 s10, s86, s10
	s_addc_u32 s11, s87, 0
	v_lshrrev_b32_e32 v222, 6, v0
	v_and_b32_e32 v223, 63, v0
	v_lshlrev_b32_e32 v222, 5, v222
	v_lshrrev_b32_e32 v224, 2, v223
	v_add_u32_e32 v222, v222, v224
	v_and_b32_e32 v223, 3, v223
	v_lshlrev_b32_e32 v223, 7, v223
	v_lshl_add_u32 v222, v222, 12, v223
	v_add_u32_e32 v223, 0x10000, v222
	global_load_dword v224, v222, s[10:11]
	global_load_dword v225, v223, s[10:11]
	s_branch .Lpf9_back
